# gate_gemm loads pipelined one ks-step ahead; dilmerge OG loads hoisted above LSE wait
# speedup vs baseline: 1.0042x; 1.0008x over previous
.LBB0_523:
	v_lshl_add_u64 v[18:19], v[16:17], 0, s[4:5]
	v_add_co_u32_e32 v22, vcc, 0x13100000, v18
	v_lshl_add_u64 v[20:21], v[10:11], 0, s[4:5]
	s_nop 0
	v_addc_co_u32_e32 v23, vcc, 0, v19, vcc
	v_add_co_u32_e32 v18, vcc, 0x4200000, v20
	s_nop 1
	v_addc_co_u32_e32 v19, vcc, 0, v21, vcc
	v_add_co_u32_e32 v20, vcc, 0x4210000, v20
	s_nop 1
	v_addc_co_u32_e32 v21, vcc, 0, v21, vcc
	global_load_dwordx4 v[26:29], v[22:23], off
	global_load_dwordx4 v[30:33], v[18:19], off
	global_load_dwordx4 v[34:37], v[20:21], off
	global_load_dwordx4 v[38:41], v[22:23], off offset:64
	global_load_dwordx4 v[42:45], v[18:19], off offset:64
	global_load_dwordx4 v[46:49], v[20:21], off offset:64
	s_waitcnt vmcnt(4)
	v_mfma_f32_16x16x32_bf16 v[6:9], v[26:29], v[30:33], v[6:9]
	s_waitcnt vmcnt(3)
	v_mfma_f32_16x16x32_bf16 v[2:5], v[26:29], v[34:37], v[2:5]
	global_load_dwordx4 v[26:29], v[22:23], off offset:128
	global_load_dwordx4 v[30:33], v[18:19], off offset:128
	global_load_dwordx4 v[34:37], v[20:21], off offset:128
	s_waitcnt vmcnt(4)
	v_mfma_f32_16x16x32_bf16 v[6:9], v[38:41], v[42:45], v[6:9]
	s_waitcnt vmcnt(3)
	v_mfma_f32_16x16x32_bf16 v[2:5], v[38:41], v[46:49], v[2:5]
	global_load_dwordx4 v[38:41], v[22:23], off offset:192
	global_load_dwordx4 v[42:45], v[18:19], off offset:192
	global_load_dwordx4 v[46:49], v[20:21], off offset:192
	s_waitcnt vmcnt(4)
	v_mfma_f32_16x16x32_bf16 v[6:9], v[26:29], v[30:33], v[6:9]
	s_waitcnt vmcnt(3)
	v_mfma_f32_16x16x32_bf16 v[2:5], v[26:29], v[34:37], v[2:5]
	global_load_dwordx4 v[26:29], v[22:23], off offset:256
	global_load_dwordx4 v[30:33], v[18:19], off offset:256
	global_load_dwordx4 v[34:37], v[20:21], off offset:256
	s_waitcnt vmcnt(4)
	v_mfma_f32_16x16x32_bf16 v[6:9], v[38:41], v[42:45], v[6:9]
	s_waitcnt vmcnt(3)
	v_mfma_f32_16x16x32_bf16 v[2:5], v[38:41], v[46:49], v[2:5]
	global_load_dwordx4 v[38:41], v[22:23], off offset:320
	global_load_dwordx4 v[42:45], v[18:19], off offset:320
	global_load_dwordx4 v[46:49], v[20:21], off offset:320
	s_waitcnt vmcnt(4)
	v_mfma_f32_16x16x32_bf16 v[6:9], v[26:29], v[30:33], v[6:9]
	s_waitcnt vmcnt(3)
	v_mfma_f32_16x16x32_bf16 v[2:5], v[26:29], v[34:37], v[2:5]
	global_load_dwordx4 v[26:29], v[22:23], off offset:384
	global_load_dwordx4 v[30:33], v[18:19], off offset:384
	global_load_dwordx4 v[34:37], v[20:21], off offset:384
	s_waitcnt vmcnt(4)
	v_mfma_f32_16x16x32_bf16 v[6:9], v[38:41], v[42:45], v[6:9]
	s_waitcnt vmcnt(3)
	v_mfma_f32_16x16x32_bf16 v[2:5], v[38:41], v[46:49], v[2:5]
	global_load_dwordx4 v[38:41], v[22:23], off offset:448
	global_load_dwordx4 v[42:45], v[18:19], off offset:448
	global_load_dwordx4 v[46:49], v[20:21], off offset:448
	s_waitcnt vmcnt(4)
	v_mfma_f32_16x16x32_bf16 v[6:9], v[26:29], v[30:33], v[6:9]
	s_waitcnt vmcnt(3)
	v_mfma_f32_16x16x32_bf16 v[2:5], v[26:29], v[34:37], v[2:5]
	s_waitcnt vmcnt(1)
	v_mfma_f32_16x16x32_bf16 v[6:9], v[38:41], v[42:45], v[6:9]
	s_waitcnt vmcnt(0)
	v_mfma_f32_16x16x32_bf16 v[2:5], v[38:41], v[46:49], v[2:5]
	s_add_u32 s4, s4, 0x200
	s_addc_u32 s5, s5, 0
	s_cmpk_eq_i32 s4, 0x1000
	s_cbranch_scc0 .LBB0_523
	v_lshl_or_b32 v18, v24, 4, v25
	v_mov_b64_e32 v[16:17], s[30:31]
	v_ashrrev_i32_e32 v19, 31, v18
	v_mad_i64_i32 v[20:21], s[4:5], v18, s78, v[16:17]
	v_lshl_add_u64 v[38:39], v[20:21], 0, v[0:1]
	v_lshlrev_b64 v[20:21], 7, v[18:19]
	v_lshl_add_u64 v[42:43], s[18:19], 0, v[20:21]
	global_load_dwordx4 v[20:23], v[42:43], off offset:48
	global_load_dwordx4 v[26:29], v[42:43], off offset:32
	global_load_dwordx4 v[30:33], v[42:43], off
	global_load_dwordx4 v[34:37], v[42:43], off offset:16
	v_mov_b32_e32 v52, 0x358637bd
	s_mov_b64 s[8:9], 0x3000
	v_lshl_add_u64 v[40:41], v[38:39], 0, s[8:9]
	v_readlane_b32 s1, v255, 4
	s_waitcnt vmcnt(3)
	v_add_f32_e32 v48, v20, v21
	v_add_f32_e32 v50, v22, v23
	s_waitcnt vmcnt(1)
	v_mov_b32_e32 v44, v30
	s_waitcnt vmcnt(0)
	v_mov_b32_e32 v45, v34
	v_mov_b32_e32 v34, v31
	v_pk_add_f32 v[30:31], v[44:45], v[34:35]
	v_mov_b32_e32 v34, v32
	v_mov_b32_e32 v35, v36
	v_mov_b32_e32 v36, v33
	v_pk_add_f32 v[32:33], v[34:35], v[36:37]
	v_add_u32_e32 v14, s1, v14
	v_pk_add_f32 v[30:31], v[30:31], v[32:33]
	s_nop 0
	v_add_f32_e32 v15, 0, v30
	v_add_f32_e32 v44, v15, v31
	v_mov_b32_e32 v30, v27
	v_mov_b32_e32 v31, v28
	v_mov_b32_e32 v27, v29
	v_pk_add_f32 v[26:27], v[30:31], v[26:27]
	s_nop 0
	v_pk_add_f32 v[46:47], v[26:27], v[26:27] op_sel:[0,1] op_sel_hi:[1,0]
	global_load_dwordx4 v[20:23], v[42:43], off offset:112
	global_load_dwordx4 v[26:29], v[42:43], off offset:96
	global_load_dwordx4 v[30:33], v[42:43], off offset:80
	global_load_dwordx4 v[34:37], v[42:43], off offset:64
	s_waitcnt vmcnt(2)
	v_add_f32_e32 v26, v26, v27
	v_add_f32_e32 v28, v28, v29
	s_waitcnt vmcnt(0)
	v_mov_b32_e32 v45, v34
	v_mov_b32_e32 v47, v35
	v_mov_b32_e32 v49, v36
	v_mov_b32_e32 v51, v37
	v_pk_add_f32 v[34:35], v[44:45], v[46:47]
	v_pk_add_f32 v[36:37], v[48:49], v[50:51]
	v_mov_b32_e32 v27, v22
	v_pk_add_f32 v[34:35], v[34:35], v[36:37]
	v_mov_b32_e32 v36, v31
	v_mov_b32_e32 v37, v32
	v_mov_b32_e32 v31, v33
	v_pk_add_f32 v[30:31], v[36:37], v[30:31]
	v_pk_add_f32 v[34:35], v[34:35], v[34:35] op_sel:[0,1] op_sel_hi:[1,0]
	v_pk_add_f32 v[30:31], v[30:31], v[30:31] op_sel:[0,1] op_sel_hi:[1,0]
	v_mov_b32_e32 v35, v20
	v_mov_b32_e32 v31, v21
	v_mov_b32_e32 v29, v23
	v_pk_add_f32 v[20:21], v[34:35], v[30:31]
	v_pk_add_f32 v[22:23], v[26:27], v[28:29]
	v_or_b32_e32 v26, 1, v18
	v_pk_add_f32 v[20:21], v[20:21], v[22:23]
	v_ashrrev_i32_e32 v27, 31, v26
	v_add_f32_e32 v15, v20, v21
	v_fmamk_f32 v15, v15, 0x3a000000, v52
	v_cmp_gt_f32_e32 vcc, s0, v15
	v_mul_f32_e32 v19, 0x4b800000, v15
	s_nop 0
	v_cndmask_b32_e32 v15, v15, v19, vcc
	v_rsq_f32_e32 v15, v15
	s_nop 0
	v_mul_f32_e32 v19, 0x45800000, v15
	v_cndmask_b32_e32 v15, v15, v19, vcc
	v_mul_f32_e32 v6, v6, v15
	v_bfe_u32 v19, v6, 16, 1
	v_add_co_u32_e32 v20, vcc, s96, v38
	v_add3_u32 v6, v6, v19, s92
	s_nop 0
	v_addc_co_u32_e32 v21, vcc, 0, v39, vcc
	v_mul_f32_e32 v2, v2, v15
	global_store_short_d16_hi v[20:21], v6, off
	v_bfe_u32 v6, v2, 16, 1
	v_add3_u32 v2, v2, v6, s92
	v_mad_i64_i32 v[20:21], s[4:5], v26, s78, v[16:17]
	v_lshlrev_b64 v[26:27], 7, v[26:27]
	global_store_short_d16_hi v[40:41], v2, off offset:32
	v_lshl_add_u64 v[42:43], s[18:19], 0, v[26:27]
	global_load_dwordx4 v[26:29], v[42:43], off offset:48
	global_load_dwordx4 v[30:33], v[42:43], off offset:32
	global_load_dwordx4 v[34:37], v[42:43], off
	global_load_dwordx4 v[38:41], v[42:43], off offset:16
	v_lshl_add_u64 v[22:23], v[20:21], 0, v[0:1]
	v_lshl_add_u64 v[20:21], v[22:23], 0, s[8:9]
	s_waitcnt vmcnt(3)
	v_add_f32_e32 v48, v26, v27
	v_add_f32_e32 v50, v28, v29
	s_waitcnt vmcnt(1)
	v_mov_b32_e32 v44, v34
	s_waitcnt vmcnt(0)
	v_mov_b32_e32 v45, v38
	v_mov_b32_e32 v38, v35
	v_pk_add_f32 v[34:35], v[44:45], v[38:39]
	v_mov_b32_e32 v38, v36
	v_mov_b32_e32 v39, v40
	v_mov_b32_e32 v40, v37
	v_pk_add_f32 v[36:37], v[38:39], v[40:41]
	s_nop 0
	v_pk_add_f32 v[34:35], v[34:35], v[36:37]
	s_nop 0
	v_add_f32_e32 v2, 0, v34
	v_add_f32_e32 v44, v2, v35
	v_mov_b32_e32 v34, v31
	v_mov_b32_e32 v35, v32
	v_mov_b32_e32 v31, v33
	v_pk_add_f32 v[30:31], v[34:35], v[30:31]
	s_nop 0
	v_pk_add_f32 v[46:47], v[30:31], v[30:31] op_sel:[0,1] op_sel_hi:[1,0]
	global_load_dwordx4 v[26:29], v[42:43], off offset:112
	global_load_dwordx4 v[30:33], v[42:43], off offset:96
	global_load_dwordx4 v[34:37], v[42:43], off offset:80
	global_load_dwordx4 v[38:41], v[42:43], off offset:64
	s_waitcnt vmcnt(2)
	v_add_f32_e32 v30, v30, v31
	v_add_f32_e32 v32, v32, v33
	s_waitcnt vmcnt(0)
	v_mov_b32_e32 v45, v38
	v_mov_b32_e32 v47, v39
	v_mov_b32_e32 v49, v40
	v_mov_b32_e32 v51, v41
	v_pk_add_f32 v[38:39], v[44:45], v[46:47]
	v_pk_add_f32 v[40:41], v[48:49], v[50:51]
	v_mov_b32_e32 v31, v28
	v_pk_add_f32 v[38:39], v[38:39], v[40:41]
	v_mov_b32_e32 v40, v35
	v_mov_b32_e32 v41, v36
	v_mov_b32_e32 v35, v37
	v_pk_add_f32 v[34:35], v[40:41], v[34:35]
	v_pk_add_f32 v[38:39], v[38:39], v[38:39] op_sel:[0,1] op_sel_hi:[1,0]
	v_pk_add_f32 v[34:35], v[34:35], v[34:35] op_sel:[0,1] op_sel_hi:[1,0]
	v_mov_b32_e32 v39, v26
	v_mov_b32_e32 v35, v27
	v_mov_b32_e32 v33, v29
	v_pk_add_f32 v[26:27], v[38:39], v[34:35]
	v_pk_add_f32 v[28:29], v[30:31], v[32:33]
	s_nop 0
	v_pk_add_f32 v[26:27], v[26:27], v[28:29]
	s_nop 0
	v_add_f32_e32 v2, v26, v27
	v_fmamk_f32 v2, v2, 0x3a000000, v52
	v_cmp_gt_f32_e32 vcc, s0, v2
	v_mul_f32_e32 v6, 0x4b800000, v2
	s_nop 0
	v_cndmask_b32_e32 v2, v2, v6, vcc
	v_rsq_f32_e32 v2, v2
	s_nop 0
	v_mul_f32_e32 v6, 0x45800000, v2
	v_cndmask_b32_e32 v2, v2, v6, vcc
	v_mul_f32_e32 v6, v7, v2
	v_mul_f32_e32 v2, v3, v2
	v_bfe_u32 v3, v2, 16, 1
	v_add3_u32 v2, v2, v3, s92
	v_bfe_u32 v7, v6, 16, 1
	global_store_short_d16_hi v[20:21], v2, off offset:32
	v_or_b32_e32 v20, 2, v18
	v_add3_u32 v15, v6, v7, s92
	v_add_co_u32_e32 v6, vcc, s96, v22
	v_ashrrev_i32_e32 v21, 31, v20
	s_nop 0
	v_addc_co_u32_e32 v7, vcc, 0, v23, vcc
	v_mad_i64_i32 v[2:3], s[4:5], v20, s78, v[16:17]
	v_lshlrev_b64 v[20:21], 7, v[20:21]
	global_store_short_d16_hi v[6:7], v15, off
	v_lshl_add_u64 v[38:39], s[18:19], 0, v[20:21]
	global_load_dwordx4 v[20:23], v[38:39], off offset:48
	global_load_dwordx4 v[26:29], v[38:39], off offset:32
	global_load_dwordx4 v[30:33], v[38:39], off
	global_load_dwordx4 v[34:37], v[38:39], off offset:16
	v_lshl_add_u64 v[6:7], v[2:3], 0, v[0:1]
	v_lshl_add_u64 v[2:3], v[6:7], 0, s[8:9]
	v_or_b32_e32 v18, 3, v18
	s_waitcnt vmcnt(3)
	v_add_f32_e32 v44, v20, v21
	v_add_f32_e32 v46, v22, v23
	s_waitcnt vmcnt(1)
	v_mov_b32_e32 v40, v30
	s_waitcnt vmcnt(0)
	v_mov_b32_e32 v41, v34
	v_mov_b32_e32 v34, v31
	v_pk_add_f32 v[30:31], v[40:41], v[34:35]
	v_mov_b32_e32 v34, v32
	v_mov_b32_e32 v35, v36
	v_mov_b32_e32 v36, v33
	v_pk_add_f32 v[32:33], v[34:35], v[36:37]
	s_nop 0
	v_pk_add_f32 v[30:31], v[30:31], v[32:33]
	s_nop 0
	v_add_f32_e32 v15, 0, v30
	v_add_f32_e32 v40, v15, v31
	v_mov_b32_e32 v30, v27
	v_mov_b32_e32 v31, v28
	v_mov_b32_e32 v27, v29
	v_pk_add_f32 v[26:27], v[30:31], v[26:27]
	s_nop 0
	v_pk_add_f32 v[42:43], v[26:27], v[26:27] op_sel:[0,1] op_sel_hi:[1,0]
	global_load_dwordx4 v[20:23], v[38:39], off offset:112
	global_load_dwordx4 v[26:29], v[38:39], off offset:96
	global_load_dwordx4 v[30:33], v[38:39], off offset:80
	global_load_dwordx4 v[34:37], v[38:39], off offset:64
	s_waitcnt vmcnt(2)
	v_add_f32_e32 v26, v26, v27
	v_add_f32_e32 v28, v28, v29
	s_waitcnt vmcnt(0)
	v_mov_b32_e32 v41, v34
	v_mov_b32_e32 v43, v35
	v_mov_b32_e32 v45, v36
	v_mov_b32_e32 v47, v37
	v_pk_add_f32 v[34:35], v[40:41], v[42:43]
	v_pk_add_f32 v[36:37], v[44:45], v[46:47]
	v_mov_b32_e32 v27, v22
	v_pk_add_f32 v[34:35], v[34:35], v[36:37]
	v_mov_b32_e32 v36, v31
	v_mov_b32_e32 v37, v32
	v_mov_b32_e32 v31, v33
	v_pk_add_f32 v[30:31], v[36:37], v[30:31]
	v_pk_add_f32 v[34:35], v[34:35], v[34:35] op_sel:[0,1] op_sel_hi:[1,0]
	v_pk_add_f32 v[30:31], v[30:31], v[30:31] op_sel:[0,1] op_sel_hi:[1,0]
	v_mov_b32_e32 v35, v20
	v_mov_b32_e32 v31, v21
	v_mov_b32_e32 v29, v23
	v_pk_add_f32 v[20:21], v[34:35], v[30:31]
	v_pk_add_f32 v[22:23], v[26:27], v[28:29]
	s_nop 0
	v_pk_add_f32 v[20:21], v[20:21], v[22:23]
	s_nop 0
	v_add_f32_e32 v15, v20, v21
	v_fmamk_f32 v15, v15, 0x3a000000, v52
	v_cmp_gt_f32_e32 vcc, s0, v15
	v_mul_f32_e32 v19, 0x4b800000, v15
	s_nop 0
	v_cndmask_b32_e32 v15, v15, v19, vcc
	v_rsq_f32_e32 v15, v15
	s_nop 0
	v_mul_f32_e32 v19, 0x45800000, v15
	v_cndmask_b32_e32 v15, v15, v19, vcc
	v_mul_f32_e32 v8, v8, v15
	v_bfe_u32 v19, v8, 16, 1
	v_add_co_u32_e32 v6, vcc, s96, v6
	v_add3_u32 v8, v8, v19, s92
	s_nop 0
	v_addc_co_u32_e32 v7, vcc, 0, v7, vcc
	v_mul_f32_e32 v4, v4, v15
	global_store_short_d16_hi v[6:7], v8, off
	v_bfe_u32 v6, v4, 16, 1
	v_add3_u32 v4, v4, v6, s92
	v_ashrrev_i32_e32 v19, 31, v18
	global_store_short_d16_hi v[2:3], v4, off offset:32
	v_mad_i64_i32 v[2:3], s[4:5], v18, s78, v[16:17]
	v_lshlrev_b64 v[16:17], 7, v[18:19]
	v_lshl_add_u64 v[34:35], s[18:19], 0, v[16:17]
	global_load_dwordx4 v[16:19], v[34:35], off offset:48
	global_load_dwordx4 v[20:23], v[34:35], off offset:32
	global_load_dwordx4 v[26:29], v[34:35], off
	global_load_dwordx4 v[30:33], v[34:35], off offset:16
	v_lshl_add_u64 v[6:7], v[2:3], 0, v[0:1]
	v_lshl_add_u64 v[2:3], v[6:7], 0, s[8:9]
	v_readlane_b32 s4, v255, 15
	v_readlane_b32 s5, v255, 16
	s_waitcnt vmcnt(3)
	v_add_f32_e32 v40, v16, v17
	v_add_f32_e32 v42, v18, v19
	s_waitcnt vmcnt(1)
	v_mov_b32_e32 v36, v26
	s_waitcnt vmcnt(0)
	v_mov_b32_e32 v37, v30
	v_mov_b32_e32 v30, v27
	v_pk_add_f32 v[26:27], v[36:37], v[30:31]
	v_mov_b32_e32 v30, v28
	v_mov_b32_e32 v31, v32
	v_mov_b32_e32 v32, v29
	v_pk_add_f32 v[28:29], v[30:31], v[32:33]
	v_add_u32_e32 v24, s4, v24
	v_pk_add_f32 v[26:27], v[26:27], v[28:29]
	s_nop 0
	v_add_f32_e32 v4, 0, v26
	v_add_f32_e32 v36, v4, v27
	v_mov_b32_e32 v26, v21
	v_mov_b32_e32 v27, v22
	v_mov_b32_e32 v21, v23
	v_pk_add_f32 v[20:21], v[26:27], v[20:21]
	s_nop 0
	v_pk_add_f32 v[38:39], v[20:21], v[20:21] op_sel:[0,1] op_sel_hi:[1,0]
	global_load_dwordx4 v[16:19], v[34:35], off offset:112
	global_load_dwordx4 v[20:23], v[34:35], off offset:96
	global_load_dwordx4 v[26:29], v[34:35], off offset:80
	global_load_dwordx4 v[30:33], v[34:35], off offset:64
	s_waitcnt vmcnt(2)
	v_add_f32_e32 v20, v20, v21
	v_add_f32_e32 v22, v22, v23
	s_waitcnt vmcnt(0)
	v_mov_b32_e32 v37, v30
	v_mov_b32_e32 v39, v31
	v_mov_b32_e32 v41, v32
	v_mov_b32_e32 v43, v33
	v_pk_add_f32 v[30:31], v[36:37], v[38:39]
	v_pk_add_f32 v[32:33], v[40:41], v[42:43]
	v_mov_b32_e32 v21, v18
	v_pk_add_f32 v[30:31], v[30:31], v[32:33]
	v_mov_b32_e32 v32, v27
	v_mov_b32_e32 v33, v28
	v_mov_b32_e32 v27, v29
	v_pk_add_f32 v[26:27], v[32:33], v[26:27]
	v_pk_add_f32 v[30:31], v[30:31], v[30:31] op_sel:[0,1] op_sel_hi:[1,0]
	v_pk_add_f32 v[26:27], v[26:27], v[26:27] op_sel:[0,1] op_sel_hi:[1,0]
	v_mov_b32_e32 v31, v16
	v_mov_b32_e32 v27, v17
	v_mov_b32_e32 v23, v19
	v_pk_add_f32 v[16:17], v[30:31], v[26:27]
	v_pk_add_f32 v[18:19], v[20:21], v[22:23]
	s_nop 0
	v_pk_add_f32 v[16:17], v[16:17], v[18:19]
	s_nop 0
	v_add_f32_e32 v4, v16, v17
	v_fmamk_f32 v4, v4, 0x3a000000, v52
	v_cmp_gt_f32_e32 vcc, s0, v4
	v_mul_f32_e32 v8, 0x4b800000, v4
	s_nop 0
	v_cndmask_b32_e32 v4, v4, v8, vcc
	v_rsq_f32_e32 v4, v4
	s_nop 0
	v_mul_f32_e32 v8, 0x45800000, v4
	v_cndmask_b32_e32 v4, v4, v8, vcc
	v_add_co_u32_e32 v6, vcc, 0x3000, v6
	v_mul_f32_e32 v8, v9, v4
	s_nop 0
	v_addc_co_u32_e32 v7, vcc, 0, v7, vcc
	v_mul_f32_e32 v4, v5, v4
	v_bfe_u32 v9, v8, 16, 1
	v_bfe_u32 v5, v4, 16, 1
	v_cmp_lt_i32_e32 vcc, s21, v24
	v_add3_u32 v8, v8, v9, s92
	v_add3_u32 v4, v4, v5, s92
	s_or_b64 s[36:37], vcc, s[36:37]
	global_store_short_d16_hi v[6:7], v8, off
	global_store_short_d16_hi v[2:3], v4, off offset:32
	s_andn2_b64 exec, exec, s[36:37]
	s_cbranch_execnz .LBB0_522

.LBB0_1051:
	s_waitcnt lgkmcnt(0)
	v_lshl_add_u64 v[2:3], s[18:19], 0, v[12:13]
	v_add_co_u32_e32 v4, vcc, 0x2a100000, v2
	s_waitcnt vmcnt(19)
	v_lshl_add_u64 v[18:19], s[18:19], 0, v[10:11]
	v_addc_co_u32_e32 v5, vcc, 0, v3, vcc
	global_load_dword v0, v[4:5], off
	v_add_co_u32_e32 v4, vcc, 0x2a120000, v2
	s_mov_b32 s1, 0x28900000
	s_nop 0
	v_addc_co_u32_e32 v5, vcc, 0, v3, vcc
	v_add_co_u32_e32 v2, vcc, 0x2a140000, v2
	global_load_dword v4, v[4:5], off
	s_nop 0
	v_addc_co_u32_e32 v3, vcc, 0, v3, vcc
	global_load_dword v2, v[2:3], off
	v_add_co_u32_e32 v30, vcc, 0x28900000, v18
	s_nop 1
	v_addc_co_u32_e32 v31, vcc, 0, v19, vcc
	global_load_dwordx4 v[132:135], v[30:31], off
	v_add_co_u32_e32 v32, vcc, 0x29100000, v18
	s_nop 1
	v_addc_co_u32_e32 v33, vcc, 0, v19, vcc
	global_load_dwordx4 v[136:139], v[32:33], off
	v_add_co_u32_e32 v140, vcc, 0x29900000, v18
	s_nop 1
	v_addc_co_u32_e32 v141, vcc, 0, v19, vcc
	global_load_dwordx4 v[36:39], v[140:141], off
	v_add_u32_e32 v6, s12, v6
	v_lshl_add_u64 v[10:11], v[10:11], 0, s[20:21]
	v_lshl_add_u64 v[12:13], v[12:13], 0, s[22:23]
	s_waitcnt vmcnt(3)
	v_max3_f32 v3, v0, v4, v2
	v_sub_f32_e32 v0, v0, v3
	v_mul_f32_e32 v0, 0x3fb8aa3b, v0
	v_sub_f32_e32 v4, v4, v3
	v_exp_f32_e32 v0, v0
	v_mul_f32_e32 v4, 0x3fb8aa3b, v4
	v_sub_f32_e32 v2, v2, v3
	v_exp_f32_e32 v7, v4
	v_mul_f32_e32 v2, 0x3fb8aa3b, v2
	v_exp_f32_e32 v23, v2
	v_add_f32_e32 v5, 0, v0
	v_add_f32_e32 v4, v7, v5
	v_add_f32_e32 v2, v23, v4
	v_div_scale_f32 v3, s[4:5], v2, v2, 1.0
	v_rcp_f32_e32 v4, v3
	s_nop 0
	v_fma_f32 v5, -v3, v4, 1.0
	v_fmac_f32_e32 v4, v5, v4
	v_div_scale_f32 v5, vcc, 1.0, v2, 1.0
	v_mul_f32_e32 v14, v5, v4
	v_fma_f32 v15, -v3, v14, v5
	v_fmac_f32_e32 v14, v15, v4
	v_fma_f32 v3, -v3, v14, v5
	v_div_fmas_f32 v3, v3, v4, v14
	v_div_fixup_f32 v24, v3, v2, 1.0
	v_add_co_u32_e32 v2, vcc, s1, v18
	s_mov_b32 s1, 0x29100000
	s_nop 0
	v_addc_co_u32_e32 v3, vcc, 0, v19, vcc
	v_add_co_u32_e32 v14, vcc, s1, v18
	s_mov_b32 s1, 0x29900000
	s_nop 0
	v_addc_co_u32_e32 v15, vcc, 0, v19, vcc
	s_waitcnt vmcnt(2)
	v_mov_b32_e32 v2, v132
	v_mov_b32_e32 v3, v133
	v_mov_b32_e32 v4, v134
	v_mov_b32_e32 v5, v135
	v_add_co_u32_e32 v18, vcc, s1, v18
	s_waitcnt vmcnt(1)
	v_mov_b32_e32 v14, v136
	v_mov_b32_e32 v15, v137
	v_mov_b32_e32 v16, v138
	v_mov_b32_e32 v17, v139
	s_nop 0
	v_addc_co_u32_e32 v19, vcc, 0, v19, vcc
	s_waitcnt vmcnt(0)
	v_mov_b32_e32 v18, v36
	v_mov_b32_e32 v19, v37
	v_mov_b32_e32 v20, v38
	v_mov_b32_e32 v21, v39
	v_mul_f32_e32 v0, v0, v24
	v_mul_f32_e32 v22, v7, v24
	v_mul_f32_e32 v24, v23, v24
	s_movk_i32 s1, 0x1fff
	v_cmp_lt_i32_e32 vcc, s1, v6
	s_or_b64 s[30:31], vcc, s[30:31]
	s_waitcnt vmcnt(2)
	v_lshlrev_b32_e32 v27, 16, v3
	v_lshlrev_b32_e32 v26, 16, v2
	v_and_b32_e32 v3, 0xffff0000, v3
	v_and_b32_e32 v2, 0xffff0000, v2
	v_pk_fma_f32 v[2:3], v[0:1], v[2:3], 0 op_sel_hi:[0,1,0]
	s_waitcnt vmcnt(1)
	v_lshlrev_b32_e32 v29, 16, v15
	v_lshlrev_b32_e32 v28, 16, v14
	v_and_b32_e32 v15, 0xffff0000, v15
	v_and_b32_e32 v14, 0xffff0000, v14
	v_pk_fma_f32 v[26:27], v[0:1], v[26:27], 0 op_sel_hi:[0,1,0]
	v_pk_fma_f32 v[2:3], v[22:23], v[14:15], v[2:3] op_sel_hi:[0,1,1]
	s_waitcnt vmcnt(0)
	v_lshlrev_b32_e32 v15, 16, v19
	v_lshlrev_b32_e32 v14, 16, v18
	v_and_b32_e32 v19, 0xffff0000, v19
	v_and_b32_e32 v18, 0xffff0000, v18
	v_pk_fma_f32 v[26:27], v[22:23], v[28:29], v[26:27] op_sel_hi:[0,1,1]
	v_pk_fma_f32 v[2:3], v[24:25], v[18:19], v[2:3] op_sel_hi:[0,1,1]
	v_lshlrev_b32_e32 v19, 16, v5
	v_lshlrev_b32_e32 v18, 16, v4
	v_and_b32_e32 v5, 0xffff0000, v5
	v_and_b32_e32 v4, 0xffff0000, v4
	v_pk_fma_f32 v[14:15], v[24:25], v[14:15], v[26:27] op_sel_hi:[0,1,1]
	v_pk_fma_f32 v[18:19], v[0:1], v[18:19], 0 op_sel_hi:[0,1,0]
	v_pk_fma_f32 v[4:5], v[0:1], v[4:5], 0 op_sel_hi:[0,1,0]
	v_lshlrev_b32_e32 v27, 16, v17
	v_lshlrev_b32_e32 v26, 16, v16
	v_and_b32_e32 v17, 0xffff0000, v17
	v_and_b32_e32 v16, 0xffff0000, v16
	v_pk_fma_f32 v[18:19], v[22:23], v[26:27], v[18:19] op_sel_hi:[0,1,1]
	v_pk_fma_f32 v[4:5], v[22:23], v[16:17], v[4:5] op_sel_hi:[0,1,1]
	v_lshlrev_b32_e32 v17, 16, v21
	v_lshlrev_b32_e32 v16, 16, v20
	v_pk_fma_f32 v[16:17], v[24:25], v[16:17], v[18:19] op_sel_hi:[0,1,1]
	v_and_b32_e32 v19, 0xffff0000, v21
	v_and_b32_e32 v18, 0xffff0000, v20
	v_pk_fma_f32 v[4:5], v[24:25], v[18:19], v[4:5] op_sel_hi:[0,1,1]
	v_bfe_u32 v0, v5, 16, 1
	v_bfe_u32 v7, v4, 16, 1
	v_bfe_u32 v18, v3, 16, 1
	v_bfe_u32 v19, v2, 16, 1
	v_add3_u32 v2, v2, v19, s92
	v_add3_u32 v3, v3, v18, s92
	v_add3_u32 v4, v4, v7, s92
	v_add3_u32 v0, v5, v0, s92
	v_bfe_u32 v5, v14, 16, 1
	v_bfe_u32 v7, v15, 16, 1
	v_bfe_u32 v18, v16, 16, 1
	v_bfe_u32 v19, v17, 16, 1
	v_add3_u32 v17, v17, v19, s92
	v_add3_u32 v16, v16, v18, s92
	v_add3_u32 v7, v15, v7, s92
	v_add3_u32 v5, v14, v5, s92
	v_lshrrev_b32_e32 v14, 16, v5
	v_lshrrev_b32_e32 v7, 16, v7
	v_lshrrev_b32_e32 v15, 16, v16
	v_lshrrev_b32_e32 v5, 16, v17
	v_and_or_b32 v5, v0, s97, v5
	v_and_or_b32 v4, v4, s97, v15
	v_and_or_b32 v3, v3, s97, v7
	v_and_or_b32 v2, v2, s97, v14
	v_lshl_add_u64 v[14:15], s[18:19], 0, v[8:9]
	v_lshl_add_u64 v[8:9], v[8:9], 0, s[14:15]
	global_store_dwordx4 v[14:15], v[2:5], off
	s_andn2_b64 exec, exec, s[30:31]
	s_cbranch_execnz .LBB0_1051
